# grid barrier: the globally last XCD leader increments every XCD's release generation itself (no per-XCD leader hop between TOPGEN and XGEN)
# speedup vs baseline: 1.0022x; 1.0022x over previous
; __device__ __forceinline__ unsigned xb_ld(unsigned* p)              { return __hip_atomic_load(p, __ATOMIC_RELAXED, __HIP_MEMORY_SCOPE_AGENT); }
; __device__ __forceinline__ unsigned xb_add(unsigned* p, unsigned v) { return __hip_atomic_fetch_add(p, v, __ATOMIC_RELAXED, __HIP_MEMORY_SCOPE_AGENT); }
; #define XB_SPIN(cond, bar) do { unsigned _sp = 0; while (cond) { __builtin_amdgcn_s_sleep(1); \
;     if ((++_sp & 255u) == 0u) { if (xb_ld(&(bar)[XB_TMO])) break; if (_sp > XB_SPIN_CAP) { atomicAdd(&(bar)[XB_TMO], 1u); break; } } } } while (0)
; __device__ __forceinline__ void xcd_barrier(const XcdBarrier& b) {
;     ...
;             const unsigned og = xb_add(&bar[XB_TOP], 1u);
;             const unsigned tg = og / nx;
;             if (og + 1u == (tg + 1u) * nx) xb_add(&bar[XB_TOPGEN], 1u);
;             else XB_SPIN(xb_ld(&bar[XB_TOPGEN]) == tg, bar);
;             __builtin_amdgcn_fence(__ATOMIC_ACQUIRE, "agent");
;             xb_add(&bar[XB_XGEN(b.x)], 1u);
;             asm volatile("s_waitcnt vmcnt(0)" ::: "memory");
.LBB0_122:
	s_or_b64 exec, exec, s[8:9]
	s_and_saveexec_b64 s[8:9], s[16:17]
	s_cbranch_execz .LBB0_124
	v_mov_b32_e32 v1, 1
	global_atomic_add v[2:3], v1, off
	v_mov_b32_e32 v6, 0x3400
	global_atomic_add v6, v1, s[30:31]
	global_atomic_add v6, v1, s[30:31] offset:256
	global_atomic_add v6, v1, s[30:31] offset:512
	global_atomic_add v6, v1, s[30:31] offset:768
	global_atomic_add v6, v1, s[30:31] offset:1024
	global_atomic_add v6, v1, s[30:31] offset:1280
	global_atomic_add v6, v1, s[30:31] offset:1536
	global_atomic_add v6, v1, s[30:31] offset:1792
	global_atomic_add v6, v1, s[30:31] offset:2048
	global_atomic_add v6, v1, s[30:31] offset:2304
	global_atomic_add v6, v1, s[30:31] offset:2560
	global_atomic_add v6, v1, s[30:31] offset:2816
	global_atomic_add v6, v1, s[30:31] offset:3072
	global_atomic_add v6, v1, s[30:31] offset:3328
	global_atomic_add v6, v1, s[30:31] offset:3584
	global_atomic_add v6, v1, s[30:31] offset:3840
.LBB0_124:
	s_or_b64 exec, exec, s[8:9]
	s_mov_b64 s[8:9], exec
	v_mbcnt_lo_u32_b32 v1, s8, 0
	v_mbcnt_hi_u32_b32 v1, s9, v1
	v_cmp_eq_u32_e32 vcc, 0, v1
	s_waitcnt vmcnt(0)
	buffer_inv sc1
	s_and_saveexec_b64 s[14:15], vcc
	s_cbranch_execz .LBB0_126
	s_bcnt1_i32_b64 s3, s[8:9]
	v_mov_b32_e32 v1, 0x2000
	v_mov_b32_e32 v2, s3
.LBB0_126:
	s_or_b64 exec, exec, s[14:15]
	s_waitcnt vmcnt(0)

; __device__ __forceinline__ unsigned xb_add(unsigned* p, unsigned v) { return __hip_atomic_fetch_add(p, v, __ATOMIC_RELAXED, __HIP_MEMORY_SCOPE_AGENT); }
; __device__ __forceinline__ void xcd_barrier(const XcdBarrier& b) {
;     ...
;             __builtin_amdgcn_fence(__ATOMIC_ACQUIRE, "agent");
;             xb_add(&bar[XB_XGEN(b.x)], 1u);
;             asm volatile("s_waitcnt vmcnt(0)" ::: "memory");
.LBB0_217:
	s_or_b64 exec, exec, s[8:9]
	s_mov_b64 s[8:9], exec
	v_mbcnt_lo_u32_b32 v1, s8, 0
	v_mbcnt_hi_u32_b32 v1, s9, v1
	v_cmp_eq_u32_e32 vcc, 0, v1
	s_waitcnt vmcnt(0)
	buffer_inv sc1
	s_and_saveexec_b64 s[14:15], vcc
	s_cbranch_execz .LBB0_219
	s_bcnt1_i32_b64 s3, s[8:9]
	v_mov_b32_e32 v1, 0x2000
	v_mov_b32_e32 v2, s3
.LBB0_219:
	s_or_b64 exec, exec, s[14:15]
	s_waitcnt vmcnt(0)

; __device__ __forceinline__ unsigned xb_ld(unsigned* p)              { return __hip_atomic_load(p, __ATOMIC_RELAXED, __HIP_MEMORY_SCOPE_AGENT); }
; __device__ __forceinline__ unsigned xb_add(unsigned* p, unsigned v) { return __hip_atomic_fetch_add(p, v, __ATOMIC_RELAXED, __HIP_MEMORY_SCOPE_AGENT); }
; #define XB_SPIN(cond, bar) do { unsigned _sp = 0; while (cond) { __builtin_amdgcn_s_sleep(1); \
;     if ((++_sp & 255u) == 0u) { if (xb_ld(&(bar)[XB_TMO])) break; if (_sp > XB_SPIN_CAP) { atomicAdd(&(bar)[XB_TMO], 1u); break; } } } } while (0)
; __device__ __forceinline__ void xcd_barrier(const XcdBarrier& b) {
;     ...
;             const unsigned og = xb_add(&bar[XB_TOP], 1u);
;             const unsigned tg = og / nx;
;             if (og + 1u == (tg + 1u) * nx) xb_add(&bar[XB_TOPGEN], 1u);
;             else XB_SPIN(xb_ld(&bar[XB_TOPGEN]) == tg, bar);
;             __builtin_amdgcn_fence(__ATOMIC_ACQUIRE, "agent");
;             xb_add(&bar[XB_XGEN(b.x)], 1u);
;             asm volatile("s_waitcnt vmcnt(0)" ::: "memory");
.LBB0_520:
	s_or_b64 exec, exec, s[8:9]
	s_and_saveexec_b64 s[8:9], s[12:13]
	s_cbranch_execz .LBB0_522
	v_mov_b32_e32 v1, 1
	global_atomic_add v[2:3], v1, off
	v_mov_b32_e32 v6, 0x3400
	global_atomic_add v6, v1, s[30:31]
	global_atomic_add v6, v1, s[30:31] offset:256
	global_atomic_add v6, v1, s[30:31] offset:512
	global_atomic_add v6, v1, s[30:31] offset:768
	global_atomic_add v6, v1, s[30:31] offset:1024
	global_atomic_add v6, v1, s[30:31] offset:1280
	global_atomic_add v6, v1, s[30:31] offset:1536
	global_atomic_add v6, v1, s[30:31] offset:1792
	global_atomic_add v6, v1, s[30:31] offset:2048
	global_atomic_add v6, v1, s[30:31] offset:2304
	global_atomic_add v6, v1, s[30:31] offset:2560
	global_atomic_add v6, v1, s[30:31] offset:2816
	global_atomic_add v6, v1, s[30:31] offset:3072
	global_atomic_add v6, v1, s[30:31] offset:3328
	global_atomic_add v6, v1, s[30:31] offset:3584
	global_atomic_add v6, v1, s[30:31] offset:3840
.LBB0_522:
	s_or_b64 exec, exec, s[8:9]
	s_mov_b64 s[8:9], exec
	v_mbcnt_lo_u32_b32 v1, s8, 0
	v_mbcnt_hi_u32_b32 v1, s9, v1
	v_cmp_eq_u32_e32 vcc, 0, v1
	s_waitcnt vmcnt(0)
	buffer_inv sc1
	s_and_saveexec_b64 s[10:11], vcc
	s_cbranch_execz .LBB0_524
	s_bcnt1_i32_b64 s3, s[8:9]
	v_mov_b32_e32 v1, 0x2000
	v_mov_b32_e32 v2, s3
.LBB0_524:
	s_or_b64 exec, exec, s[10:11]
	s_waitcnt vmcnt(0)

; __device__ __forceinline__ unsigned xb_add(unsigned* p, unsigned v) { return __hip_atomic_fetch_add(p, v, __ATOMIC_RELAXED, __HIP_MEMORY_SCOPE_AGENT); }
; __device__ __forceinline__ void xcd_barrier(const XcdBarrier& b) {
;     ...
;             __builtin_amdgcn_fence(__ATOMIC_ACQUIRE, "agent");
;             xb_add(&bar[XB_XGEN(b.x)], 1u);
;             asm volatile("s_waitcnt vmcnt(0)" ::: "memory");
.LBB0_594:
	s_or_b64 exec, exec, s[8:9]
	s_mov_b64 s[8:9], exec
	v_mbcnt_lo_u32_b32 v1, s8, 0
	v_mbcnt_hi_u32_b32 v1, s9, v1
	v_cmp_eq_u32_e32 vcc, 0, v1
	s_waitcnt vmcnt(0)
	buffer_inv sc1
	s_and_saveexec_b64 s[10:11], vcc
	s_cbranch_execz .LBB0_596
	s_bcnt1_i32_b64 s3, s[8:9]
	v_mov_b32_e32 v1, 0x2000
	v_mov_b32_e32 v2, s3
.LBB0_596:
	s_or_b64 exec, exec, s[10:11]
	s_waitcnt vmcnt(0)

; __device__ __forceinline__ unsigned xb_add(unsigned* p, unsigned v) { return __hip_atomic_fetch_add(p, v, __ATOMIC_RELAXED, __HIP_MEMORY_SCOPE_AGENT); }
; __device__ __forceinline__ void xcd_barrier(const XcdBarrier& b) {
;     ...
;             __builtin_amdgcn_fence(__ATOMIC_ACQUIRE, "agent");
;             xb_add(&bar[XB_XGEN(b.x)], 1u);
;             asm volatile("s_waitcnt vmcnt(0)" ::: "memory");
.LBB0_693:
	s_or_b64 exec, exec, s[8:9]
	s_mov_b64 s[8:9], exec
	v_mbcnt_lo_u32_b32 v1, s8, 0
	v_mbcnt_hi_u32_b32 v1, s9, v1
	v_cmp_eq_u32_e32 vcc, 0, v1
	s_waitcnt vmcnt(0)
	buffer_inv sc1
	s_and_saveexec_b64 s[10:11], vcc
	s_cbranch_execz .LBB0_695
	s_bcnt1_i32_b64 s3, s[8:9]
	v_mov_b32_e32 v1, 0x2000
	v_mov_b32_e32 v2, s3
.LBB0_695:
	s_or_b64 exec, exec, s[10:11]
	s_waitcnt vmcnt(0)

; __device__ __forceinline__ unsigned xb_add(unsigned* p, unsigned v) { return __hip_atomic_fetch_add(p, v, __ATOMIC_RELAXED, __HIP_MEMORY_SCOPE_AGENT); }
; __device__ __forceinline__ void xcd_barrier(const XcdBarrier& b) {
;     ...
;             __builtin_amdgcn_fence(__ATOMIC_ACQUIRE, "agent");
;             xb_add(&bar[XB_XGEN(b.x)], 1u);
;             asm volatile("s_waitcnt vmcnt(0)" ::: "memory");
.LBB0_786:
	s_or_b64 exec, exec, s[8:9]
	s_mov_b64 s[8:9], exec
	v_mbcnt_lo_u32_b32 v1, s8, 0
	v_mbcnt_hi_u32_b32 v1, s9, v1
	v_cmp_eq_u32_e32 vcc, 0, v1
	s_waitcnt vmcnt(0)
	buffer_inv sc1
	s_and_saveexec_b64 s[10:11], vcc
	s_cbranch_execz .LBB0_788
	s_bcnt1_i32_b64 s3, s[8:9]
	v_mov_b32_e32 v1, 0x2000
	v_mov_b32_e32 v2, s3
.LBB0_788:
	s_or_b64 exec, exec, s[10:11]
	s_waitcnt vmcnt(0)

; __device__ __forceinline__ unsigned xb_ld(unsigned* p)              { return __hip_atomic_load(p, __ATOMIC_RELAXED, __HIP_MEMORY_SCOPE_AGENT); }
; __device__ __forceinline__ unsigned xb_add(unsigned* p, unsigned v) { return __hip_atomic_fetch_add(p, v, __ATOMIC_RELAXED, __HIP_MEMORY_SCOPE_AGENT); }
; #define XB_SPIN(cond, bar) do { unsigned _sp = 0; while (cond) { __builtin_amdgcn_s_sleep(1); \
;     if ((++_sp & 255u) == 0u) { if (xb_ld(&(bar)[XB_TMO])) break; if (_sp > XB_SPIN_CAP) { atomicAdd(&(bar)[XB_TMO], 1u); break; } } } } while (0)
; __device__ __forceinline__ void xcd_barrier(const XcdBarrier& b) {
;     ...
;             const unsigned og = xb_add(&bar[XB_TOP], 1u);
;             const unsigned tg = og / nx;
;             if (og + 1u == (tg + 1u) * nx) xb_add(&bar[XB_TOPGEN], 1u);
;             else XB_SPIN(xb_ld(&bar[XB_TOPGEN]) == tg, bar);
;             __builtin_amdgcn_fence(__ATOMIC_ACQUIRE, "agent");
;             xb_add(&bar[XB_XGEN(b.x)], 1u);
;             asm volatile("s_waitcnt vmcnt(0)" ::: "memory");
.LBB0_862:
	s_or_b64 exec, exec, s[6:7]
	s_and_saveexec_b64 s[6:7], s[10:11]
	s_cbranch_execz .LBB0_864
	v_mov_b32_e32 v1, 1
	global_atomic_add v[2:3], v1, off
	v_mov_b32_e32 v6, 0x3400
	global_atomic_add v6, v1, s[30:31]
	global_atomic_add v6, v1, s[30:31] offset:256
	global_atomic_add v6, v1, s[30:31] offset:512
	global_atomic_add v6, v1, s[30:31] offset:768
	global_atomic_add v6, v1, s[30:31] offset:1024
	global_atomic_add v6, v1, s[30:31] offset:1280
	global_atomic_add v6, v1, s[30:31] offset:1536
	global_atomic_add v6, v1, s[30:31] offset:1792
	global_atomic_add v6, v1, s[30:31] offset:2048
	global_atomic_add v6, v1, s[30:31] offset:2304
	global_atomic_add v6, v1, s[30:31] offset:2560
	global_atomic_add v6, v1, s[30:31] offset:2816
	global_atomic_add v6, v1, s[30:31] offset:3072
	global_atomic_add v6, v1, s[30:31] offset:3328
	global_atomic_add v6, v1, s[30:31] offset:3584
	global_atomic_add v6, v1, s[30:31] offset:3840
.LBB0_864:
	s_or_b64 exec, exec, s[6:7]
	s_mov_b64 s[6:7], exec
	v_mbcnt_lo_u32_b32 v1, s6, 0
	v_mbcnt_hi_u32_b32 v1, s7, v1
	v_cmp_eq_u32_e32 vcc, 0, v1
	s_waitcnt vmcnt(0)
	buffer_inv sc1
	s_and_saveexec_b64 s[8:9], vcc
	s_cbranch_execz .LBB0_866
	s_bcnt1_i32_b64 s3, s[6:7]
	v_mov_b32_e32 v1, 0x2000
	v_mov_b32_e32 v2, s3
.LBB0_866:
	s_or_b64 exec, exec, s[8:9]
	s_waitcnt vmcnt(0)
